# P1: rs loads requested at the top of the unit's last K-iteration, epilogue waits vmcnt(16) (on top of v23)
# baseline (speedup 1.0000x reference)
; #define PG8_STAGE(bufoff, gbase, voff) do { _Pragma("unroll") for (int _i = 0; _i < 2; ++_i) \
;         __builtin_amdgcn_global_load_lds((const unsigned*)((const char*)(gbase) + (voff)[_i]), (PG8_LAS unsigned*)(lds + (bufoff) + ldsw + _i * 8192), 16, 0, 0); } while (0)
; #define PG8_WAIT_V(n) asm volatile("s_waitcnt vmcnt(" #n ")" ::: "memory")
; #define PG8_BAR __builtin_amdgcn_s_barrier()
;     __device__ __forceinline__ void operator()(const f32x4 (&acc)[2][2][4][2], const Unit& u, int wr, int wc, int fr, int fq) const {
;     ...
;                 const int row = row0 + ai * HALF + m * 16; const float rsv = rs[row] * sc;
; template <class Epi, class Sched, bool ALIGN_EPI = false, bool SP2 = false>
; __device__ __forceinline__ void gemm_phase(PG8_LAS unsigned char* lds, const Gemm g, const Sched& S, const Epi& E, int wid_in) {
;     ...
;         for (int t = 0; t < nt; t += 2) {
;             const bool last = (t == nt - 2);
;             if constexpr (Epi::HAS_MID) { if (t == nt / 2) E.mid(acc, cur, wr, wc, fr, fq); }
;             const char* a1 = cA + (size_t)(t + 1) * kstep;
;             const char* a2 = last ? nA : cA + (size_t)(t + 2) * kstep; const char* b2 = last ? nB : cB + (size_t)(t + 2) * kstep;
;             const char* a3 = a2 + kstep; const char* b3 = b2 + kstep;
;             if (last && has_next) S.a_ready(nxt);
;             if constexpr (SP2) {
;             PG8_LDB(B0, 0, 0); PG8_LDB(B1, 0, 1); PG8_SCHED; PG8_LDA(At, 0, 0); PG8_STAGE(PG8_SA(1, 1), a1 + hstep, voffA);
;             PG8_WAIT_V(8); PG8_WAIT_L(0); PG8_BAR; PG8_MMA(0, 0, At, B0); PG8_MMA(0, 1, At, B1); PG8_BAR; PG8_SCHED;
;             PG8_LDA(At, 0, 1); PG8_STAGE(PG8_SB(0, 0), b2, voffB); PG8_STAGE(PG8_SB(0, 1), b2 + hstep, voffB); PG8_STAGE(PG8_SA(0, 0), a2, voffA);
;             PG8_WAIT_V(8); PG8_WAIT_L(0); PG8_BAR; PG8_MMA(1, 0, At, B0); PG8_MMA(1, 1, At, B1); PG8_BAR; PG8_SCHED;
;             PG8_LDB(B0, 1, 0); PG8_LDB(B1, 1, 1); PG8_SCHED; PG8_LDA(At, 1, 0); PG8_STAGE(PG8_SA(0, 1), a2 + hstep, voffA);
;             PG8_WAIT_V(8); PG8_WAIT_L(0); PG8_BAR; PG8_MMA(0, 0, At, B0); PG8_MMA(0, 1, At, B1); PG8_BAR; PG8_SCHED;
;             PG8_LDA(At, 1, 1); PG8_STAGE(PG8_SB(1, 0), b3, voffB); PG8_STAGE(PG8_SB(1, 1), b3 + hstep, voffB); PG8_STAGE(PG8_SA(1, 0), a3, voffA);
;             PG8_WAIT_V(8); PG8_WAIT_L(0); PG8_BAR; PG8_MMA(1, 0, At, B0); PG8_MMA(1, 1, At, B1); PG8_BAR; PG8_SCHED;
.LBB0_227:
	ds_read_b128 v[128:131], v171
	ds_read_b128 v[132:135], v171 offset:1024
	ds_read_b128 v[158:161], v171 offset:2048
	ds_read_b128 v[162:165], v171 offset:3072
	ds_read_b128 v[174:177], v172
	ds_read_b128 v[178:181], v172 offset:1024
	ds_read_b128 v[182:185], v172 offset:2048
	ds_read_b128 v[186:189], v172 offset:3072
	s_add_u32 s88, s68, 0xfffc0080
	s_addc_u32 s89, s69, -1
	s_cmp_eq_u32 s94, 12
	s_cselect_b32 s91, s3, s89
	s_cselect_b32 s90, s5, s88
	s_cselect_b32 s89, s81, s93
	s_cselect_b32 s88, s83, s92
	s_cbranch_scc0 .Lp1_nors
	v_lshl_add_u32 v238, s2, 8, v168
	v_ashrrev_i32_e32 v239, 31, v238
	v_lshl_add_u64 v[240:241], v[238:239], 2, s[6:7]
	global_load_dword v230, v[240:241], off
	global_load_dword v231, v[240:241], off offset:64
	global_load_dword v232, v[240:241], off offset:128
	global_load_dword v233, v[240:241], off offset:192
	global_load_dword v234, v[240:241], off offset:512
	global_load_dword v235, v[240:241], off offset:576
	global_load_dword v236, v[240:241], off offset:640
	global_load_dword v237, v[240:241], off offset:704
.Lp1_nors:
	v_lshl_add_u64 v[166:167], s[68:69], 0, v[150:151]
	s_add_i32 m0, s34, 0xc000
	ds_read_b128 v[190:193], v173
	ds_read_b128 v[194:197], v173 offset:1024
	ds_read_b128 v[198:201], v173 offset:2048
	ds_read_b128 v[202:205], v173 offset:3072
	ds_read_b128 v[206:209], v173 offset:4096
	ds_read_b128 v[210:213], v173 offset:5120
	ds_read_b128 v[214:217], v173 offset:6144
	ds_read_b128 v[218:221], v173 offset:7168
	global_load_lds_dwordx4 v[166:167], off
	v_lshl_add_u64 v[166:167], s[68:69], 0, v[152:153]
	s_add_i32 m0, s34, 0xe000
	s_nop 0
	global_load_lds_dwordx4 v[166:167], off
	s_waitcnt vmcnt(8)
	s_waitcnt lgkmcnt(0)
	s_barrier
	s_setprio 1
	s_waitcnt lgkmcnt(0)
	v_mfma_f32_16x16x32_bf16 v[124:127], v[128:131], v[190:193], v[124:127]
	v_mfma_f32_16x16x32_bf16 v[120:123], v[158:161], v[190:193], v[120:123]
	v_mfma_f32_16x16x32_bf16 v[108:111], v[128:131], v[198:201], v[108:111]
	v_mfma_f32_16x16x32_bf16 v[104:107], v[158:161], v[198:201], v[104:107]
	v_mfma_f32_16x16x32_bf16 v[92:95], v[128:131], v[206:209], v[92:95]
	v_mfma_f32_16x16x32_bf16 v[88:91], v[158:161], v[206:209], v[88:91]
	v_mfma_f32_16x16x32_bf16 v[76:79], v[128:131], v[214:217], v[76:79]
	v_mfma_f32_16x16x32_bf16 v[72:75], v[158:161], v[214:217], v[72:75]
	v_mfma_f32_16x16x32_bf16 v[124:127], v[132:135], v[194:197], v[124:127]
	v_mfma_f32_16x16x32_bf16 v[120:123], v[162:165], v[194:197], v[120:123]
	v_mfma_f32_16x16x32_bf16 v[108:111], v[132:135], v[202:205], v[108:111]
	v_mfma_f32_16x16x32_bf16 v[104:107], v[162:165], v[202:205], v[104:107]
	v_mfma_f32_16x16x32_bf16 v[92:95], v[132:135], v[210:213], v[92:95]
	v_mfma_f32_16x16x32_bf16 v[88:91], v[162:165], v[210:213], v[88:91]
	v_mfma_f32_16x16x32_bf16 v[76:79], v[132:135], v[218:221], v[76:79]
	v_mfma_f32_16x16x32_bf16 v[72:75], v[162:165], v[218:221], v[72:75]
	s_setprio 0
	s_setprio 1
	v_mfma_f32_16x16x32_bf16 v[116:119], v[174:177], v[190:193], v[116:119]
	v_mfma_f32_16x16x32_bf16 v[112:115], v[182:185], v[190:193], v[112:115]
	v_mfma_f32_16x16x32_bf16 v[100:103], v[174:177], v[198:201], v[100:103]
	v_mfma_f32_16x16x32_bf16 v[96:99], v[182:185], v[198:201], v[96:99]
	v_mfma_f32_16x16x32_bf16 v[84:87], v[174:177], v[206:209], v[84:87]
	v_mfma_f32_16x16x32_bf16 v[80:83], v[182:185], v[206:209], v[80:83]
	v_mfma_f32_16x16x32_bf16 v[68:71], v[174:177], v[214:217], v[68:71]
	v_mfma_f32_16x16x32_bf16 v[64:67], v[182:185], v[214:217], v[64:67]
	v_mfma_f32_16x16x32_bf16 v[116:119], v[178:181], v[194:197], v[116:119]
	v_mfma_f32_16x16x32_bf16 v[112:115], v[186:189], v[194:197], v[112:115]
	v_mfma_f32_16x16x32_bf16 v[100:103], v[178:181], v[202:205], v[100:103]
	v_mfma_f32_16x16x32_bf16 v[96:99], v[186:189], v[202:205], v[96:99]
	v_mfma_f32_16x16x32_bf16 v[84:87], v[178:181], v[210:213], v[84:87]
	v_mfma_f32_16x16x32_bf16 v[80:83], v[186:189], v[210:213], v[80:83]
	v_mfma_f32_16x16x32_bf16 v[68:71], v[178:181], v[218:221], v[68:71]
	v_mfma_f32_16x16x32_bf16 v[64:67], v[186:189], v[218:221], v[64:67]
	s_setprio 0
	s_barrier
	s_add_i32 s95, s70, s12
	v_lshl_add_u64 v[166:167], s[88:89], 0, v[138:139]
	s_mov_b32 m0, s95
	ds_read_b128 v[190:193], v173 offset:16384
	ds_read_b128 v[194:197], v173 offset:17408
	ds_read_b128 v[198:201], v173 offset:18432
	ds_read_b128 v[202:205], v173 offset:19456
	ds_read_b128 v[206:209], v173 offset:20480
	ds_read_b128 v[210:213], v173 offset:21504
	ds_read_b128 v[214:217], v173 offset:22528
	ds_read_b128 v[218:221], v173 offset:23552
	global_load_lds_dwordx4 v[166:167], off
	s_add_i32 m0, s95, 0x2000
	s_add_u32 vcc_lo, s88, 0x40000
	v_lshl_add_u64 v[222:223], s[88:89], 0, v[142:143]
	s_addc_u32 vcc_hi, s89, 0
	s_add_i32 s95, s71, s12
	global_load_lds_dwordx4 v[222:223], off
	v_lshl_add_u64 v[224:225], vcc, 0, v[138:139]
	s_mov_b32 m0, s95
	v_lshl_add_u64 v[226:227], s[90:91], 0, v[140:141]
	global_load_lds_dwordx4 v[224:225], off
	v_lshl_add_u64 v[224:225], vcc, 0, v[142:143]
	s_add_i32 m0, s95, 0x2000
	s_nop 0
	global_load_lds_dwordx4 v[224:225], off
	v_lshl_add_u64 v[224:225], s[90:91], 0, v[136:137]
	s_mov_b32 m0, s34
	s_nop 0
	global_load_lds_dwordx4 v[224:225], off
	s_mov_b32 m0, s35
	s_nop 0
	global_load_lds_dwordx4 v[226:227], off
	s_waitcnt vmcnt(8)
	s_waitcnt lgkmcnt(0)
	s_barrier
; #define PG8_STAGE(bufoff, gbase, voff) do { _Pragma("unroll") for (int _i = 0; _i < 2; ++_i) \
;         __builtin_amdgcn_global_load_lds((const unsigned*)((const char*)(gbase) + (voff)[_i]), (PG8_LAS unsigned*)(lds + (bufoff) + ldsw + _i * 8192), 16, 0, 0); } while (0)
; #define PG8_LDA(dst, b, h) do { _Pragma("unroll") for (int m = 0; m < 4; ++m) _Pragma("unroll") for (int k = 0; k < 2; ++k) dst[m][k] = *(const PG8_LAS bf16x8*)(lds + PG8_SA(b, h) + aoff + m * 2048 + k * 1024); } while (0)
; #define PG8_LDB(dst, b, h) do { _Pragma("unroll") for (int n = 0; n < 2; ++n) _Pragma("unroll") for (int k = 0; k < 2; ++k) dst[n][k] = *(const PG8_LAS bf16x8*)(lds + PG8_SB(b, h) + boff + n * 2048 + k * 1024); } while (0)
; #define PG8_MMA(ai, bj, At, Bt) do { __builtin_amdgcn_s_setprio(1); _Pragma("unroll") for (int m = 0; m < 4; ++m) _Pragma("unroll") for (int n = 0; n < 2; ++n) _Pragma("unroll") for (int k = 0; k < 2; ++k) \
;         acc[ai][bj][m][n] = __builtin_amdgcn_mfma_f32_16x16x32_bf16(Bt[n][k], At[m][k], acc[ai][bj][m][n], 0, 0, 0); __builtin_amdgcn_s_setprio(0); } while (0)
; #define PG8_BAR __builtin_amdgcn_s_barrier()
; template <class Epi, class Sched, bool ALIGN_EPI = false, bool SP2 = false>
; __device__ __forceinline__ void gemm_phase(PG8_LAS unsigned char* lds, const Gemm g, const Sched& S, const Epi& E, int wid_in) {
;     ...
;             PG8_LDB(B0, 0, 0); PG8_LDB(B1, 0, 1); PG8_SCHED; PG8_LDA(At, 0, 0); PG8_STAGE(PG8_SA(1, 1), a1 + hstep, voffA);
;             PG8_WAIT_V(8); PG8_WAIT_L(0); PG8_BAR; PG8_MMA(0, 0, At, B0); PG8_MMA(0, 1, At, B1); PG8_BAR; PG8_SCHED;
;             PG8_LDA(At, 0, 1); PG8_STAGE(PG8_SB(0, 0), b2, voffB); PG8_STAGE(PG8_SB(0, 1), b2 + hstep, voffB); PG8_STAGE(PG8_SA(0, 0), a2, voffA);
;             PG8_WAIT_V(8); PG8_WAIT_L(0); PG8_BAR; PG8_MMA(1, 0, At, B0); PG8_MMA(1, 1, At, B1); PG8_BAR; PG8_SCHED;
;             PG8_LDB(B0, 1, 0); PG8_LDB(B1, 1, 1); PG8_SCHED; PG8_LDA(At, 1, 0); PG8_STAGE(PG8_SA(0, 1), a2 + hstep, voffA);
;             PG8_WAIT_V(8); PG8_WAIT_L(0); PG8_BAR; PG8_MMA(0, 0, At, B0); PG8_MMA(0, 1, At, B1); PG8_BAR; PG8_SCHED;
;             PG8_LDA(At, 1, 1); PG8_STAGE(PG8_SB(1, 0), b3, voffB); PG8_STAGE(PG8_SB(1, 1), b3 + hstep, voffB); PG8_STAGE(PG8_SA(1, 0), a3, voffA);
;             PG8_WAIT_V(8); PG8_WAIT_L(0); PG8_BAR; PG8_MMA(1, 0, At, B0); PG8_MMA(1, 1, At, B1); PG8_BAR; PG8_SCHED;
	s_setprio 1
	s_waitcnt lgkmcnt(0)
	v_mfma_f32_16x16x32_bf16 v[60:63], v[128:131], v[190:193], v[60:63]
	v_mfma_f32_16x16x32_bf16 v[56:59], v[158:161], v[190:193], v[56:59]
	v_mfma_f32_16x16x32_bf16 v[44:47], v[128:131], v[198:201], v[44:47]
	v_mfma_f32_16x16x32_bf16 v[40:43], v[158:161], v[198:201], v[40:43]
	v_mfma_f32_16x16x32_bf16 v[28:31], v[128:131], v[206:209], v[28:31]
	v_mfma_f32_16x16x32_bf16 v[24:27], v[158:161], v[206:209], v[24:27]
	v_mfma_f32_16x16x32_bf16 v[12:15], v[128:131], v[214:217], v[12:15]
	v_mfma_f32_16x16x32_bf16 v[8:11], v[158:161], v[214:217], v[8:11]
	v_mfma_f32_16x16x32_bf16 v[60:63], v[132:135], v[194:197], v[60:63]
	v_mfma_f32_16x16x32_bf16 v[56:59], v[162:165], v[194:197], v[56:59]
	v_mfma_f32_16x16x32_bf16 v[44:47], v[132:135], v[202:205], v[44:47]
	v_mfma_f32_16x16x32_bf16 v[40:43], v[162:165], v[202:205], v[40:43]
	v_mfma_f32_16x16x32_bf16 v[28:31], v[132:135], v[210:213], v[28:31]
	v_mfma_f32_16x16x32_bf16 v[24:27], v[162:165], v[210:213], v[24:27]
	v_mfma_f32_16x16x32_bf16 v[12:15], v[132:135], v[218:221], v[12:15]
	v_mfma_f32_16x16x32_bf16 v[8:11], v[162:165], v[218:221], v[8:11]
	s_setprio 0
	s_setprio 1
	v_mfma_f32_16x16x32_bf16 v[52:55], v[174:177], v[190:193], v[52:55]
	v_mfma_f32_16x16x32_bf16 v[48:51], v[182:185], v[190:193], v[48:51]
	v_mfma_f32_16x16x32_bf16 v[36:39], v[174:177], v[198:201], v[36:39]
	v_mfma_f32_16x16x32_bf16 v[32:35], v[182:185], v[198:201], v[32:35]
	v_mfma_f32_16x16x32_bf16 v[20:23], v[174:177], v[206:209], v[20:23]
	v_mfma_f32_16x16x32_bf16 v[16:19], v[182:185], v[206:209], v[16:19]
	v_mfma_f32_16x16x32_bf16 v[4:7], v[174:177], v[214:217], v[4:7]
	v_mfma_f32_16x16x32_bf16 v[0:3], v[182:185], v[214:217], v[0:3]
	v_mfma_f32_16x16x32_bf16 v[52:55], v[178:181], v[194:197], v[52:55]
	v_mfma_f32_16x16x32_bf16 v[48:51], v[186:189], v[194:197], v[48:51]
	v_mfma_f32_16x16x32_bf16 v[36:39], v[178:181], v[202:205], v[36:39]
	v_mfma_f32_16x16x32_bf16 v[32:35], v[186:189], v[202:205], v[32:35]
	v_mfma_f32_16x16x32_bf16 v[20:23], v[178:181], v[210:213], v[20:23]
	v_mfma_f32_16x16x32_bf16 v[16:19], v[186:189], v[210:213], v[16:19]
	v_mfma_f32_16x16x32_bf16 v[4:7], v[178:181], v[218:221], v[4:7]
	v_mfma_f32_16x16x32_bf16 v[0:3], v[186:189], v[218:221], v[0:3]
	s_setprio 0
	s_barrier
	s_add_i32 s95, 0, 0x18000
	v_add_u32_e32 v144, s95, v169
	s_add_i32 vcc_lo, 0, 0x1c000
	ds_read_b128 v[128:131], v144
	ds_read_b128 v[132:135], v144 offset:1024
	ds_read_b128 v[158:161], v144 offset:2048
	ds_read_b128 v[162:165], v144 offset:3072
	v_add_u32_e32 v144, vcc_lo, v169
	ds_read_b128 v[174:177], v144
	ds_read_b128 v[178:181], v144 offset:1024
	ds_read_b128 v[182:185], v144 offset:2048
	ds_read_b128 v[186:189], v144 offset:3072
	s_add_u32 s90, s90, 0x40000
	s_addc_u32 s91, s91, 0
	s_mov_b32 m0, s61
	v_lshl_add_u64 v[228:229], s[90:91], 0, v[136:137]
	ds_read_b128 v[190:193], v173 offset:32768
	ds_read_b128 v[194:197], v173 offset:33792
	ds_read_b128 v[198:201], v173 offset:34816
	ds_read_b128 v[202:205], v173 offset:35840
	ds_read_b128 v[206:209], v173 offset:36864
	ds_read_b128 v[210:213], v173 offset:37888
	ds_read_b128 v[214:217], v173 offset:38912
	ds_read_b128 v[218:221], v173 offset:39936
	global_load_lds_dwordx4 v[228:229], off
	v_lshl_add_u64 v[228:229], s[90:91], 0, v[140:141]
	s_mov_b32 m0, s62
	s_nop 0
	global_load_lds_dwordx4 v[228:229], off
	s_waitcnt vmcnt(8)
	s_waitcnt lgkmcnt(0)
	s_barrier
	s_setprio 1
	s_waitcnt lgkmcnt(0)
	v_mfma_f32_16x16x32_bf16 v[124:127], v[128:131], v[190:193], v[124:127]
	v_mfma_f32_16x16x32_bf16 v[120:123], v[158:161], v[190:193], v[120:123]
	v_mfma_f32_16x16x32_bf16 v[108:111], v[128:131], v[198:201], v[108:111]
	v_mfma_f32_16x16x32_bf16 v[104:107], v[158:161], v[198:201], v[104:107]
	v_mfma_f32_16x16x32_bf16 v[92:95], v[128:131], v[206:209], v[92:95]
	v_mfma_f32_16x16x32_bf16 v[88:91], v[158:161], v[206:209], v[88:91]
	v_mfma_f32_16x16x32_bf16 v[76:79], v[128:131], v[214:217], v[76:79]
	v_mfma_f32_16x16x32_bf16 v[72:75], v[158:161], v[214:217], v[72:75]
	v_mfma_f32_16x16x32_bf16 v[124:127], v[132:135], v[194:197], v[124:127]
	v_mfma_f32_16x16x32_bf16 v[120:123], v[162:165], v[194:197], v[120:123]
	v_mfma_f32_16x16x32_bf16 v[108:111], v[132:135], v[202:205], v[108:111]
	v_mfma_f32_16x16x32_bf16 v[104:107], v[162:165], v[202:205], v[104:107]
	v_mfma_f32_16x16x32_bf16 v[92:95], v[132:135], v[210:213], v[92:95]
	v_mfma_f32_16x16x32_bf16 v[88:91], v[162:165], v[210:213], v[88:91]
	v_mfma_f32_16x16x32_bf16 v[76:79], v[132:135], v[218:221], v[76:79]
	v_mfma_f32_16x16x32_bf16 v[72:75], v[162:165], v[218:221], v[72:75]
	s_setprio 0
	s_setprio 1
	v_mfma_f32_16x16x32_bf16 v[116:119], v[174:177], v[190:193], v[116:119]
	v_mfma_f32_16x16x32_bf16 v[112:115], v[182:185], v[190:193], v[112:115]
	v_mfma_f32_16x16x32_bf16 v[100:103], v[174:177], v[198:201], v[100:103]
	v_mfma_f32_16x16x32_bf16 v[96:99], v[182:185], v[198:201], v[96:99]
	v_mfma_f32_16x16x32_bf16 v[84:87], v[174:177], v[206:209], v[84:87]
	v_mfma_f32_16x16x32_bf16 v[80:83], v[182:185], v[206:209], v[80:83]
	v_mfma_f32_16x16x32_bf16 v[68:71], v[174:177], v[214:217], v[68:71]
	v_mfma_f32_16x16x32_bf16 v[64:67], v[182:185], v[214:217], v[64:67]
	v_mfma_f32_16x16x32_bf16 v[116:119], v[178:181], v[194:197], v[116:119]
	v_mfma_f32_16x16x32_bf16 v[112:115], v[186:189], v[194:197], v[112:115]
	v_mfma_f32_16x16x32_bf16 v[100:103], v[178:181], v[202:205], v[100:103]
	v_mfma_f32_16x16x32_bf16 v[96:99], v[186:189], v[202:205], v[96:99]
	v_mfma_f32_16x16x32_bf16 v[84:87], v[178:181], v[210:213], v[84:87]
	v_mfma_f32_16x16x32_bf16 v[80:83], v[186:189], v[210:213], v[80:83]
	v_mfma_f32_16x16x32_bf16 v[68:71], v[178:181], v[218:221], v[68:71]
	v_mfma_f32_16x16x32_bf16 v[64:67], v[186:189], v[218:221], v[64:67]
	s_setprio 0
	s_barrier
; #define PG8_STAGE(bufoff, gbase, voff) do { _Pragma("unroll") for (int _i = 0; _i < 2; ++_i) \
;         __builtin_amdgcn_global_load_lds((const unsigned*)((const char*)(gbase) + (voff)[_i]), (PG8_LAS unsigned*)(lds + (bufoff) + ldsw + _i * 8192), 16, 0, 0); } while (0)
; #define PG8_BAR __builtin_amdgcn_s_barrier()
; template <class Epi, class Sched, bool ALIGN_EPI = false, bool SP2 = false>
; __device__ __forceinline__ void gemm_phase(PG8_LAS unsigned char* lds, const Gemm g, const Sched& S, const Epi& E, int wid_in) {
;     ...
;             PG8_LDB(B0, 1, 0); PG8_LDB(B1, 1, 1); PG8_SCHED; PG8_LDA(At, 1, 0); PG8_STAGE(PG8_SA(0, 1), a2 + hstep, voffA);
;             PG8_WAIT_V(8); PG8_WAIT_L(0); PG8_BAR; PG8_MMA(0, 0, At, B0); PG8_MMA(0, 1, At, B1); PG8_BAR; PG8_SCHED;
;             PG8_LDA(At, 1, 1); PG8_STAGE(PG8_SB(1, 0), b3, voffB); PG8_STAGE(PG8_SB(1, 1), b3 + hstep, voffB); PG8_STAGE(PG8_SA(1, 0), a3, voffA);
;             PG8_WAIT_V(8); PG8_WAIT_L(0); PG8_BAR; PG8_MMA(1, 0, At, B0); PG8_MMA(1, 1, At, B1); PG8_BAR; PG8_SCHED;
;             } else {
;             PG8_LDB(B0, 0, 0); PG8_SCHED; PG8_LDA(At, 0, 0); PG8_STAGE(PG8_SA(1, 1), a1 + hstep, voffA);
;             PG8_WAIT_L(8); PG8_BAR; PG8_WAIT_L(0); PG8_MMA(0, 0, At, B0); PG8_BAR; PG8_SCHED;
;             PG8_LDB(B1, 0, 1); PG8_STAGE(PG8_SB(0, 0), b2, voffB);
;             PG8_BAR; PG8_WAIT_L(0); PG8_MMA(0, 1, At, B1); PG8_BAR;
;             PG8_LDA(At, 0, 1); PG8_STAGE(PG8_SA(0, 0), a2, voffA);
;             PG8_BAR; PG8_WAIT_L(0); PG8_MMA(1, 0, At, B0); PG8_BAR; PG8_SCHED;
;             PG8_STAGE(PG8_SB(0, 1), b2 + hstep, voffB);
;             PG8_WAIT_V(6); PG8_BAR; PG8_MMA(1, 1, At, B1); PG8_BAR;
;             PG8_LDB(B0, 1, 0); PG8_SCHED; PG8_LDA(At, 1, 0); PG8_STAGE(PG8_SA(0, 1), a2 + hstep, voffA);
;             PG8_WAIT_L(8); PG8_BAR; PG8_WAIT_L(0); PG8_MMA(0, 0, At, B0); PG8_BAR; PG8_SCHED;
;             PG8_LDB(B1, 1, 1); PG8_STAGE(PG8_SB(1, 0), b3, voffB);
;             PG8_BAR; PG8_WAIT_L(0); PG8_MMA(0, 1, At, B1); PG8_BAR;
;             PG8_LDA(At, 1, 1); PG8_STAGE(PG8_SA(1, 0), a3, voffA);
;             PG8_BAR; PG8_WAIT_L(0); PG8_MMA(1, 0, At, B0); PG8_BAR; PG8_SCHED;
;             PG8_STAGE(PG8_SB(1, 1), b3 + hstep, voffB);
;             PG8_WAIT_V(6); PG8_BAR; PG8_MMA(1, 1, At, B1); PG8_BAR;
;             }
;         }
;         if constexpr (ALIGN_EPI) { if (wr == 0) PG8_BAR; }
	s_add_i32 s90, s95, s12
	v_lshl_add_u64 v[166:167], v[166:167], 0, s[74:75]
	s_mov_b32 m0, s90
	ds_read_b128 v[190:193], v173 offset:49152
	ds_read_b128 v[194:197], v173 offset:50176
	ds_read_b128 v[198:201], v173 offset:51200
	ds_read_b128 v[202:205], v173 offset:52224
	ds_read_b128 v[206:209], v173 offset:53248
	ds_read_b128 v[210:213], v173 offset:54272
	ds_read_b128 v[214:217], v173 offset:55296
	ds_read_b128 v[218:221], v173 offset:56320
	global_load_lds_dwordx4 v[166:167], off
	s_add_i32 m0, s90, 0x2000
	s_add_u32 s88, s88, 0x40080
	v_lshl_add_u64 v[166:167], v[222:223], 0, s[74:75]
	s_addc_u32 s89, s89, 0
	s_add_i32 s90, vcc_lo, s12
	global_load_lds_dwordx4 v[166:167], off
	v_lshl_add_u64 v[166:167], s[88:89], 0, v[138:139]
	s_mov_b32 m0, s90
	s_nop 0
	global_load_lds_dwordx4 v[166:167], off
	v_lshl_add_u64 v[166:167], s[88:89], 0, v[142:143]
	s_add_i32 m0, s90, 0x2000
	s_nop 0
	global_load_lds_dwordx4 v[166:167], off
	v_lshl_add_u64 v[166:167], v[224:225], 0, s[74:75]
	s_mov_b32 m0, s64
	s_nop 0
	global_load_lds_dwordx4 v[166:167], off
	v_lshl_add_u64 v[166:167], v[226:227], 0, s[74:75]
	s_mov_b32 m0, s65
	s_nop 0
	global_load_lds_dwordx4 v[166:167], off
	s_waitcnt vmcnt(8)
	s_waitcnt lgkmcnt(0)
	s_barrier
	s_setprio 1
	s_waitcnt lgkmcnt(0)
	v_mfma_f32_16x16x32_bf16 v[60:63], v[128:131], v[190:193], v[60:63]
	v_mfma_f32_16x16x32_bf16 v[56:59], v[158:161], v[190:193], v[56:59]
	v_mfma_f32_16x16x32_bf16 v[44:47], v[128:131], v[198:201], v[44:47]
	v_mfma_f32_16x16x32_bf16 v[40:43], v[158:161], v[198:201], v[40:43]
	v_mfma_f32_16x16x32_bf16 v[28:31], v[128:131], v[206:209], v[28:31]
	v_mfma_f32_16x16x32_bf16 v[24:27], v[158:161], v[206:209], v[24:27]
	v_mfma_f32_16x16x32_bf16 v[12:15], v[128:131], v[214:217], v[12:15]
	v_mfma_f32_16x16x32_bf16 v[8:11], v[158:161], v[214:217], v[8:11]
	v_mfma_f32_16x16x32_bf16 v[60:63], v[132:135], v[194:197], v[60:63]
	v_mfma_f32_16x16x32_bf16 v[56:59], v[162:165], v[194:197], v[56:59]
	v_mfma_f32_16x16x32_bf16 v[44:47], v[132:135], v[202:205], v[44:47]
	v_mfma_f32_16x16x32_bf16 v[40:43], v[162:165], v[202:205], v[40:43]
	v_mfma_f32_16x16x32_bf16 v[28:31], v[132:135], v[210:213], v[28:31]
	v_mfma_f32_16x16x32_bf16 v[24:27], v[162:165], v[210:213], v[24:27]
	v_mfma_f32_16x16x32_bf16 v[12:15], v[132:135], v[218:221], v[12:15]
	v_mfma_f32_16x16x32_bf16 v[8:11], v[162:165], v[218:221], v[8:11]
	s_setprio 0
	s_setprio 1
	v_mfma_f32_16x16x32_bf16 v[52:55], v[174:177], v[190:193], v[52:55]
	v_mfma_f32_16x16x32_bf16 v[48:51], v[182:185], v[190:193], v[48:51]
	v_mfma_f32_16x16x32_bf16 v[36:39], v[174:177], v[198:201], v[36:39]
	v_mfma_f32_16x16x32_bf16 v[32:35], v[182:185], v[198:201], v[32:35]
	v_mfma_f32_16x16x32_bf16 v[20:23], v[174:177], v[206:209], v[20:23]
	v_mfma_f32_16x16x32_bf16 v[16:19], v[182:185], v[206:209], v[16:19]
	v_mfma_f32_16x16x32_bf16 v[4:7], v[174:177], v[214:217], v[4:7]
	v_mfma_f32_16x16x32_bf16 v[0:3], v[182:185], v[214:217], v[0:3]
	v_mfma_f32_16x16x32_bf16 v[52:55], v[178:181], v[194:197], v[52:55]
	v_mfma_f32_16x16x32_bf16 v[48:51], v[186:189], v[194:197], v[48:51]
	v_mfma_f32_16x16x32_bf16 v[36:39], v[178:181], v[202:205], v[36:39]
	v_mfma_f32_16x16x32_bf16 v[32:35], v[186:189], v[202:205], v[32:35]
	v_mfma_f32_16x16x32_bf16 v[20:23], v[178:181], v[210:213], v[20:23]
	v_mfma_f32_16x16x32_bf16 v[16:19], v[186:189], v[210:213], v[16:19]
	v_mfma_f32_16x16x32_bf16 v[4:7], v[178:181], v[218:221], v[4:7]
	v_mfma_f32_16x16x32_bf16 v[0:3], v[186:189], v[218:221], v[0:3]
	s_setprio 0
	s_barrier
	s_add_i32 s94, s94, 2
	s_add_u32 s68, s68, 0x100
	s_addc_u32 s69, s69, 0
	s_add_u32 s92, s92, 0x100
	s_addc_u32 s93, s93, 0
	s_cmp_gt_u32 s94, 13
	s_cbranch_scc0 .LBB0_227
	s_and_b64 vcc, exec, s[76:77]
	s_cbranch_vccz .LBB0_230
	s_barrier

;     __device__ __forceinline__ void operator()(const f32x4 (&acc)[2][2][4][2], const Unit& u, int wr, int wc, int fr, int fq) const {
;     ...
;         const bool ropel = dorope && !(wc & 1) && fq < 2;
;         const int row0 = u.pm * BM + wr * 64 + fr, col0 = cb + wc * 32 + 8 * fq;
; #pragma unroll
;         for (int ai = 0; ai < 2; ++ai)
; #pragma unroll
;             for (int m = 0; m < 4; ++m) {
;                 const int row = row0 + ai * HALF + m * 16; const float rsv = rs[row] * sc;
;                 f32x4 cs = (f32x4){1.f, 1.f, 1.f, 1.f}, sn = (f32x4){0.f, 0.f, 0.f, 0.f};
;                 if (ropel) { const int t = row & 8191; cs = *(const f32x4*)(rope + t * 8 + 4 * fq); sn = *(const f32x4*)(rope + 65536 + t * 8 + 4 * fq); }
;                 bf16_t* rowp = base + (size_t)row * ldc + col0;
; #pragma unroll
;                 for (int bj = 0; bj < 2; ++bj) {
;                     f32x4 v0 = acc[ai][bj][m][0] * rsv, v1 = acc[ai][bj][m][1] * rsv;
;                     if (dorope) {
;                         const f32x4 a0 = v0, a1 = v1;
;                         v0[0] = a0[0] * cs[0] - a0[1] * sn[0]; v0[1] = a0[1] * cs[0] + a0[0] * sn[0];
;                         v0[2] = a0[2] * cs[1] - a0[3] * sn[1]; v0[3] = a0[3] * cs[1] + a0[2] * sn[1];
;                         v1[0] = a1[0] * cs[2] - a1[1] * sn[2]; v1[1] = a1[1] * cs[2] + a1[0] * sn[2];
;                         v1[2] = a1[2] * cs[3] - a1[3] * sn[3]; v1[3] = a1[3] * cs[3] + a1[2] * sn[3];
.LBB0_247:
	v_lshl_add_u32 v158, s2, 8, v168
	v_ashrrev_i32_e32 v159, 31, v158
	v_lshl_add_u64 v[160:161], v[158:159], 2, s[6:7]
	s_and_b64 s[88:89], s[78:79], s[94:95]
	v_mov_b32_e32 v132, 0
	v_mov_b32_e32 v128, 1.0
	v_mov_b32_e32 v129, 1.0
	v_mov_b32_e32 v130, 1.0
	v_mov_b32_e32 v131, 1.0
	v_mov_b32_e32 v133, 0
	v_mov_b32_e32 v134, 0
	v_mov_b32_e32 v135, 0
	s_and_saveexec_b64 s[2:3], s[88:89]
	s_cbranch_execz .LBB0_249
	v_lshlrev_b32_e32 v128, 5, v158
	v_and_b32_e32 v144, 0x3f9e0, v128
	v_lshl_add_u64 v[132:133], v[148:149], 0, v[144:145]
	v_lshl_add_u64 v[128:129], v[146:147], 0, v[144:145]
	global_load_dwordx4 v[128:131], v[128:129], off
	s_nop 0
	global_load_dwordx4 v[132:135], v[132:133], off
	s_waitcnt vmcnt(0)
.LBB0_249:
	s_or_b64 exec, exec, s[2:3]
	s_waitcnt vmcnt(16)
	v_mov_b32_e32 v162, v230
	v_mul_f32_e32 v164, s81, v162
	v_cndmask_b32_e64 v144, 0, 1, s[94:95]
	v_pk_mul_f32 v[126:127], v[126:127], v[164:165] op_sel_hi:[1,0]
	v_pk_mul_f32 v[124:125], v[124:125], v[164:165] op_sel_hi:[1,0]
	v_pk_mul_f32 v[122:123], v[122:123], v[164:165] op_sel_hi:[1,0]
	v_cmp_ne_u32_e64 s[2:3], 1, v144
	s_andn2_b64 vcc, exec, s[94:95]
	v_pk_mul_f32 v[120:121], v[120:121], v[164:165] op_sel_hi:[1,0]
	s_cbranch_vccnz .LBB0_251
	v_pk_mul_f32 v[162:163], v[124:125], v[132:133] op_sel:[1,0] op_sel_hi:[0,0]
	v_pk_fma_f32 v[174:175], v[124:125], v[128:129], v[162:163] op_sel_hi:[1,0,1] neg_lo:[0,0,1] neg_hi:[0,0,1]
	v_pk_fma_f32 v[124:125], v[124:125], v[128:129], v[162:163] op_sel_hi:[1,0,1]
	v_mov_b32_e32 v162, v129
	v_mov_b32_e32 v163, v133
	v_mul_f32_e32 v124, v127, v133
	v_pk_fma_f32 v[176:177], v[126:127], v[162:163], v[124:125] op_sel_hi:[1,1,0] neg_lo:[0,0,1] neg_hi:[0,0,1]
	v_mov_b32_e32 v162, v133
	v_mov_b32_e32 v163, v129
	v_mul_f32_e32 v124, v127, v129
	v_pk_fma_f32 v[126:127], v[126:127], v[162:163], v[124:125] op_sel_hi:[1,1,0]
	v_mov_b32_e32 v175, v125
	v_pk_mul_f32 v[124:125], v[120:121], v[134:135] op_sel:[1,0] op_sel_hi:[0,0]
	v_pk_fma_f32 v[178:179], v[120:121], v[130:131], v[124:125] op_sel_hi:[1,0,1] neg_lo:[0,0,1] neg_hi:[0,0,1]
	v_pk_fma_f32 v[120:121], v[120:121], v[130:131], v[124:125] op_sel_hi:[1,0,1]
	v_mov_b32_e32 v124, v131
	v_mov_b32_e32 v125, v135
	v_mul_f32_e32 v120, v123, v135
	v_pk_fma_f32 v[180:181], v[122:123], v[124:125], v[120:121] op_sel_hi:[1,1,0] neg_lo:[0,0,1] neg_hi:[0,0,1]
	v_mov_b32_e32 v124, v135
	v_mov_b32_e32 v125, v131
	v_mul_f32_e32 v120, v123, v131
	v_pk_fma_f32 v[122:123], v[122:123], v[124:125], v[120:121] op_sel_hi:[1,1,0]
	v_mov_b32_e32 v179, v121
	v_mov_b32_e32 v177, v126
	v_mov_b32_e32 v181, v122
	v_mov_b64_e32 v[124:125], v[174:175]
	v_mov_b64_e32 v[120:121], v[178:179]
	v_mov_b64_e32 v[126:127], v[176:177]
	v_mov_b64_e32 v[122:123], v[180:181]
